# b8 + s_setprio 1 around MFMA clusters in the attention k-loop
# speedup vs baseline: 1.0153x; 1.0153x over previous
.LBB0_1455:
	s_and_b32 s36, s2, 1
	s_cmp_gt_i32 s2, s45
	s_cselect_b64 s[0:1], -1, 0
	s_and_b64 s[34:35], s[0:1], exec
	s_cselect_b32 s40, s7, 0
	s_add_i32 s40, s40, s2
	v_readfirstlane_b32 s3, v117
	s_lshl_b32 s50, s40, 6
	s_add_i32 s2, s3, 31
	s_cmp_lt_i32 s2, s50
	s_cbranch_scc1 .LBB0_1470
	s_sub_i32 s3, s3, s50
	s_sub_i32 s3, s3, 63
	s_cmpk_gt_i32 s3, 0x1ff
	s_cselect_b64 s[34:35], -1, 0
	s_and_b64 s[34:35], s[0:1], s[34:35]
	s_and_b64 vcc, exec, s[34:35]
	s_cbranch_vccnz .LBB0_1470
	s_mul_i32 s37, s36, 0x2400
	v_add_u32_e32 v20, s37, v156
	v_add_u32_e32 v21, v20, v157
	v_add_u32_e32 v33, v20, v158
	ds_read_b128 v[134:137], v21
	ds_read_b128 v[138:141], v21 offset:32
	ds_read_b128 v[142:145], v21 offset:64
	ds_read_b128 v[146:149], v21 offset:96
	ds_read_b128 v[236:239], v33
	ds_read_b128 v[240:243], v33 offset:32
	ds_read_b128 v[244:247], v33 offset:64
	ds_read_b128 v[248:251], v33 offset:96
	s_cmpk_gt_i32 s3, 0x70
	s_cselect_b64 s[34:35], -1, 0
	s_and_b64 s[52:53], s[0:1], s[34:35]
	s_sub_i32 s51, s2, s50
	s_cmpk_lt_i32 s51, 0x200
	s_cselect_b64 s[2:3], -1, 0
	s_waitcnt lgkmcnt(7)
	s_setprio 1
	v_mfma_f32_32x32x16_bf16 v[0:15], v[134:137], v[80:83], 0
	s_waitcnt lgkmcnt(6)
	v_mfma_f32_32x32x16_bf16 v[0:15], v[138:141], v[84:87], v[0:15]
	s_waitcnt lgkmcnt(5)
	v_mfma_f32_32x32x16_bf16 v[0:15], v[142:145], v[88:91], v[0:15]
	s_waitcnt lgkmcnt(4)
	v_mfma_f32_32x32x16_bf16 v[0:15], v[146:149], v[92:95], v[0:15]
	s_waitcnt lgkmcnt(3)
	v_mfma_f32_32x32x16_bf16 v[16:31], v[236:239], v[80:83], 0
	s_waitcnt lgkmcnt(2)
	v_mfma_f32_32x32x16_bf16 v[16:31], v[240:243], v[84:87], v[16:31]
	s_waitcnt lgkmcnt(1)
	v_mfma_f32_32x32x16_bf16 v[16:31], v[244:247], v[88:91], v[16:31]
	v_cndmask_b32_e64 v33, 0, 1, s[34:35]
	s_waitcnt lgkmcnt(0)
	v_mfma_f32_32x32x16_bf16 v[16:31], v[248:251], v[92:95], v[16:31]
	s_setprio 0
	v_cndmask_b32_e64 v34, 0, 1, s[2:3]
	s_and_b64 s[2:3], s[52:53], exec
	v_readfirstlane_b32 s2, v34
	v_readfirstlane_b32 s3, v33
	s_cselect_b32 s2, s2, s3
	s_bitcmp1_b32 s2, 0
	s_cselect_b64 s[34:35], -1, 0
	s_xor_b64 s[34:35], s[34:35], -1
	s_mov_b64 s[2:3], -1
	s_and_b64 vcc, exec, s[34:35]
	s_nop 1
	s_cbranch_vccz .Lfa_fast
	v_or_b32_e32 v125, s50, v153
	s_cmpk_lt_i32 s51, 0x110
	v_sub_u32_e32 v33, v130, v125
	s_cbranch_scc1 .LBB0_1460
	v_cmp_lt_i32_e32 vcc, s67, v33
	s_and_b64 vcc, s[0:1], vcc
	v_xad_u32 v36, v125, -1, v130
	v_cndmask_b32_e32 v35, 0, v211, vcc
	v_cmp_lt_i32_e32 vcc, s67, v36
	v_or_b32_e32 v38, 2, v125
	s_and_b64 vcc, s[0:1], vcc
	v_sub_u32_e32 v38, v130, v38
	v_med3_i32 v37, v36, -1, v209
	v_cndmask_b32_e32 v36, 0, v211, vcc
	v_med3_i32 v39, v38, -1, v209
	v_cmp_lt_i32_e32 vcc, s67, v38
	v_or_b32_e32 v38, 3, v125
	s_and_b64 vcc, s[0:1], vcc
	v_sub_u32_e32 v38, v130, v38
	v_cndmask_b32_e32 v40, 0, v211, vcc
	v_med3_i32 v41, v38, -1, v209
	v_cmp_lt_i32_e32 vcc, s67, v38
	v_or_b32_e32 v38, 8, v125
	s_and_b64 vcc, s[0:1], vcc
	v_sub_u32_e32 v38, v130, v38
	v_cndmask_b32_e32 v42, 0, v211, vcc
	v_med3_i32 v43, v38, -1, v209
	v_cmp_lt_i32_e32 vcc, s67, v38
	v_or_b32_e32 v38, 9, v125
	s_and_b64 vcc, s[0:1], vcc
	v_sub_u32_e32 v38, v130, v38
	v_cndmask_b32_e32 v44, 0, v211, vcc
	v_med3_i32 v45, v38, -1, v209
	v_cmp_lt_i32_e32 vcc, s67, v38
	v_or_b32_e32 v38, 10, v125
	s_and_b64 vcc, s[0:1], vcc
	v_sub_u32_e32 v38, v130, v38
	v_cndmask_b32_e32 v46, 0, v211, vcc
	v_med3_i32 v47, v38, -1, v209
	v_cmp_lt_i32_e32 vcc, s67, v38
	v_or_b32_e32 v38, 11, v125
	v_sub_u32_e32 v38, v130, v38
	v_med3_i32 v34, v33, -1, v209
	v_med3_i32 v127, v38, -1, v209
	v_lshl_add_u32 v34, v34, 2, s69
	v_lshl_add_u32 v37, v37, 2, s69
	v_lshl_add_u32 v41, v41, 2, s69
	v_lshl_add_u32 v43, v43, 2, s69
	v_lshl_add_u32 v45, v45, 2, s69
	v_lshl_add_u32 v47, v47, 2, s69
	v_lshl_add_u32 v127, v127, 2, s69
	v_lshl_add_u32 v39, v39, 2, s69
	ds_read_b32 v34, v34 offset:256
	ds_read_b32 v37, v37 offset:256
	ds_read_b32 v129, v39 offset:256
	ds_read_b32 v41, v41 offset:256
	ds_read_b32 v43, v43 offset:256
	ds_read_b32 v45, v45 offset:256
	ds_read_b32 v47, v47 offset:256
	ds_read_b32 v127, v127 offset:256
	s_and_b64 vcc, s[0:1], vcc
	v_cndmask_b32_e32 v131, 0, v211, vcc
	v_cmp_lt_i32_e32 vcc, s67, v38
	s_and_b64 vcc, s[0:1], vcc
	s_nop 0
	v_cndmask_b32_e32 v134, 0, v211, vcc
	s_waitcnt lgkmcnt(7)
	v_fmac_f32_e32 v34, 0x3fb8aa3b, v0
	s_waitcnt lgkmcnt(6)
	v_fmac_f32_e32 v37, 0x3fb8aa3b, v1
	v_add_f32_e32 v38, v35, v34
	v_add_f32_e32 v39, v36, v37
	s_waitcnt lgkmcnt(5)
	v_fmac_f32_e32 v129, 0x3fb8aa3b, v2
	s_waitcnt lgkmcnt(4)
	v_fmac_f32_e32 v41, 0x3fb8aa3b, v3
	v_max3_f32 v34, v38, s70, v39
	v_add_f32_e32 v36, v40, v129
	v_add_f32_e32 v37, v42, v41
	s_waitcnt lgkmcnt(3)
	v_fmac_f32_e32 v43, 0x3fb8aa3b, v4
	s_waitcnt lgkmcnt(2)
	v_fmac_f32_e32 v45, 0x3fb8aa3b, v5
	v_max3_f32 v34, v34, v36, v37
	v_add_f32_e32 v40, v44, v43
	v_add_f32_e32 v41, v46, v45
	s_waitcnt lgkmcnt(1)
	v_fmac_f32_e32 v47, 0x3fb8aa3b, v6
	s_waitcnt lgkmcnt(0)
	v_fmac_f32_e32 v127, 0x3fb8aa3b, v7
	v_max3_f32 v42, v34, v40, v41
	v_add_f32_e32 v34, v131, v47
	v_add_f32_e32 v35, v134, v127
	v_max3_f32 v42, v42, v34, v35
	v_or_b32_e32 v43, 16, v125
	v_sub_u32_e32 v43, v130, v43
	v_cmp_lt_i32_e32 vcc, s67, v43
	v_or_b32_e32 v45, 17, v125
	s_and_b64 vcc, s[0:1], vcc
	v_sub_u32_e32 v45, v130, v45
	v_med3_i32 v44, v43, -1, v209
	v_cndmask_b32_e32 v43, 0, v211, vcc
	v_cmp_lt_i32_e32 vcc, s67, v45
	v_or_b32_e32 v47, 18, v125
	s_and_b64 vcc, s[0:1], vcc
	v_sub_u32_e32 v47, v130, v47
	v_med3_i32 v46, v45, -1, v209
	v_cndmask_b32_e32 v45, 0, v211, vcc
	v_cmp_lt_i32_e32 vcc, s67, v47
	v_or_b32_e32 v129, 19, v125
	s_and_b64 vcc, s[0:1], vcc
	v_sub_u32_e32 v129, v130, v129
	v_med3_i32 v127, v47, -1, v209
	v_cndmask_b32_e32 v47, 0, v211, vcc
	v_cmp_lt_i32_e32 vcc, s67, v129
	v_or_b32_e32 v134, 24, v125
	s_and_b64 vcc, s[0:1], vcc
	v_sub_u32_e32 v134, v130, v134
	v_med3_i32 v131, v129, -1, v209
	v_cndmask_b32_e32 v129, 0, v211, vcc
	v_med3_i32 v135, v134, -1, v209
	v_cmp_lt_i32_e32 vcc, s67, v134
	v_or_b32_e32 v134, 25, v125
	s_and_b64 vcc, s[0:1], vcc
	v_sub_u32_e32 v134, v130, v134
	v_cndmask_b32_e32 v136, 0, v211, vcc
	v_med3_i32 v137, v134, -1, v209
	v_cmp_lt_i32_e32 vcc, s67, v134
	v_or_b32_e32 v134, 26, v125
	s_and_b64 vcc, s[0:1], vcc
	v_sub_u32_e32 v134, v130, v134
	v_cndmask_b32_e32 v138, 0, v211, vcc
	v_med3_i32 v139, v134, -1, v209
	v_cmp_lt_i32_e32 vcc, s67, v134
	v_or_b32_e32 v134, 27, v125
	v_sub_u32_e32 v134, v130, v134
	v_med3_i32 v140, v134, -1, v209
	v_lshl_add_u32 v44, v44, 2, s69
	v_lshl_add_u32 v46, v46, 2, s69
	v_lshl_add_u32 v127, v127, 2, s69
	v_lshl_add_u32 v131, v131, 2, s69
	v_lshl_add_u32 v137, v137, 2, s69
	v_lshl_add_u32 v139, v139, 2, s69
	v_lshl_add_u32 v140, v140, 2, s69
	v_lshl_add_u32 v135, v135, 2, s69
	ds_read_b32 v44, v44 offset:256
	ds_read_b32 v46, v46 offset:256
	ds_read_b32 v127, v127 offset:256
	ds_read_b32 v131, v131 offset:256
	ds_read_b32 v141, v135 offset:256
	ds_read_b32 v137, v137 offset:256
	ds_read_b32 v139, v139 offset:256
	ds_read_b32 v140, v140 offset:256
	s_and_b64 vcc, s[0:1], vcc
	v_cndmask_b32_e32 v142, 0, v211, vcc
	v_cmp_lt_i32_e32 vcc, s67, v134
	s_and_b64 vcc, s[0:1], vcc
	s_nop 0
	v_cndmask_b32_e32 v143, 0, v211, vcc
	s_waitcnt lgkmcnt(7)
	v_fmac_f32_e32 v44, 0x3fb8aa3b, v8
	s_waitcnt lgkmcnt(6)
	v_fmac_f32_e32 v46, 0x3fb8aa3b, v9
	v_add_f32_e32 v134, v43, v44
	v_add_f32_e32 v135, v45, v46
	s_waitcnt lgkmcnt(5)
	v_fmac_f32_e32 v127, 0x3fb8aa3b, v10
	s_waitcnt lgkmcnt(4)
	v_fmac_f32_e32 v131, 0x3fb8aa3b, v11
	v_max3_f32 v42, v42, v134, v135
	v_add_f32_e32 v44, v47, v127
	v_add_f32_e32 v45, v129, v131
	s_waitcnt lgkmcnt(3)
	v_fmac_f32_e32 v141, 0x3fb8aa3b, v12
	s_waitcnt lgkmcnt(2)
	v_fmac_f32_e32 v137, 0x3fb8aa3b, v13
	v_max3_f32 v42, v42, v44, v45
	v_add_f32_e32 v46, v136, v141
	v_add_f32_e32 v47, v138, v137
	s_waitcnt lgkmcnt(1)
	v_fmac_f32_e32 v139, 0x3fb8aa3b, v14
	s_waitcnt lgkmcnt(0)
	v_fmac_f32_e32 v140, 0x3fb8aa3b, v15
	v_max3_f32 v127, v42, v46, v47
	v_add_f32_e32 v42, v142, v139
	v_add_f32_e32 v43, v143, v140
	v_max3_f32 v127, v127, v42, v43
	v_or_b32_e32 v129, 32, v125
	v_sub_u32_e32 v129, v130, v129
	v_cmp_lt_i32_e32 vcc, s67, v129
	v_or_b32_e32 v136, 33, v125
	s_and_b64 vcc, s[0:1], vcc
	v_sub_u32_e32 v136, v130, v136
	v_med3_i32 v131, v129, -1, v209
	v_cndmask_b32_e32 v129, 0, v211, vcc
	v_cmp_lt_i32_e32 vcc, s67, v136
	v_or_b32_e32 v138, 34, v125
	s_and_b64 vcc, s[0:1], vcc
	v_sub_u32_e32 v138, v130, v138
	v_med3_i32 v137, v136, -1, v209
	v_cndmask_b32_e32 v136, 0, v211, vcc
	v_cmp_lt_i32_e32 vcc, s67, v138
	v_or_b32_e32 v140, 35, v125
	s_and_b64 vcc, s[0:1], vcc
	v_sub_u32_e32 v140, v130, v140
	v_med3_i32 v139, v138, -1, v209
	v_cndmask_b32_e32 v138, 0, v211, vcc
	v_cmp_lt_i32_e32 vcc, s67, v140
	v_or_b32_e32 v142, 40, v125
	s_and_b64 vcc, s[0:1], vcc
	v_sub_u32_e32 v142, v130, v142
	v_med3_i32 v141, v140, -1, v209
	v_cndmask_b32_e32 v140, 0, v211, vcc
	v_med3_i32 v143, v142, -1, v209
	v_cmp_lt_i32_e32 vcc, s67, v142
	v_or_b32_e32 v142, 41, v125
	s_and_b64 vcc, s[0:1], vcc
	v_sub_u32_e32 v142, v130, v142
	v_cndmask_b32_e32 v144, 0, v211, vcc
	v_med3_i32 v145, v142, -1, v209
	v_cmp_lt_i32_e32 vcc, s67, v142
	v_or_b32_e32 v142, 42, v125
	s_and_b64 vcc, s[0:1], vcc
	v_sub_u32_e32 v142, v130, v142
	v_cndmask_b32_e32 v146, 0, v211, vcc
	v_med3_i32 v147, v142, -1, v209
	v_cmp_lt_i32_e32 vcc, s67, v142
	v_or_b32_e32 v142, 43, v125
	v_sub_u32_e32 v142, v130, v142
	v_med3_i32 v148, v142, -1, v209
	v_lshl_add_u32 v131, v131, 2, s69
	v_lshl_add_u32 v137, v137, 2, s69
	v_lshl_add_u32 v139, v139, 2, s69
	v_lshl_add_u32 v141, v141, 2, s69
	v_lshl_add_u32 v145, v145, 2, s69
	v_lshl_add_u32 v147, v147, 2, s69
	v_lshl_add_u32 v148, v148, 2, s69
	v_lshl_add_u32 v143, v143, 2, s69
	ds_read_b32 v131, v131 offset:256
	ds_read_b32 v137, v137 offset:256
	ds_read_b32 v139, v139 offset:256
	ds_read_b32 v141, v141 offset:256
	ds_read_b32 v149, v143 offset:256
	ds_read_b32 v145, v145 offset:256
	ds_read_b32 v147, v147 offset:256
	ds_read_b32 v148, v148 offset:256
	s_and_b64 vcc, s[0:1], vcc
	v_cndmask_b32_e32 v150, 0, v211, vcc
	v_cmp_lt_i32_e32 vcc, s67, v142
	s_and_b64 vcc, s[0:1], vcc
	s_nop 0
	v_cndmask_b32_e32 v151, 0, v211, vcc
	s_waitcnt lgkmcnt(7)
	v_fmac_f32_e32 v131, 0x3fb8aa3b, v16
	s_waitcnt lgkmcnt(6)
	v_fmac_f32_e32 v137, 0x3fb8aa3b, v17
	v_add_f32_e32 v142, v129, v131
	v_add_f32_e32 v143, v136, v137
	s_waitcnt lgkmcnt(5)
	v_fmac_f32_e32 v139, 0x3fb8aa3b, v18
	s_waitcnt lgkmcnt(4)
	v_fmac_f32_e32 v141, 0x3fb8aa3b, v19
	v_max3_f32 v127, v127, v142, v143
	v_add_f32_e32 v138, v138, v139
	v_add_f32_e32 v139, v140, v141
	s_waitcnt lgkmcnt(3)
	v_fmac_f32_e32 v149, 0x3fb8aa3b, v20
	s_waitcnt lgkmcnt(2)
	v_fmac_f32_e32 v145, 0x3fb8aa3b, v21
	v_max3_f32 v127, v127, v138, v139
	v_add_f32_e32 v140, v144, v149
	v_add_f32_e32 v141, v146, v145
	s_waitcnt lgkmcnt(1)
	v_fmac_f32_e32 v147, 0x3fb8aa3b, v22
	s_waitcnt lgkmcnt(0)
	v_fmac_f32_e32 v148, 0x3fb8aa3b, v23
	v_max3_f32 v127, v127, v140, v141
	v_add_f32_e32 v136, v150, v147
	v_add_f32_e32 v137, v151, v148
	v_max3_f32 v127, v127, v136, v137
	v_or_b32_e32 v129, 48, v125
	v_sub_u32_e32 v129, v130, v129
	v_cmp_lt_i32_e32 vcc, s67, v129
	v_or_b32_e32 v144, 49, v125
	s_and_b64 vcc, s[0:1], vcc
	v_sub_u32_e32 v144, v130, v144
	v_med3_i32 v131, v129, -1, v209
	v_cndmask_b32_e32 v129, 0, v211, vcc
	v_cmp_lt_i32_e32 vcc, s67, v144
	v_or_b32_e32 v146, 50, v125
	s_and_b64 vcc, s[0:1], vcc
	v_sub_u32_e32 v146, v130, v146
	v_med3_i32 v145, v144, -1, v209
	v_cndmask_b32_e32 v144, 0, v211, vcc
	v_cmp_lt_i32_e32 vcc, s67, v146
	v_or_b32_e32 v148, 51, v125
	s_and_b64 vcc, s[0:1], vcc
	v_sub_u32_e32 v148, v130, v148
	v_med3_i32 v147, v146, -1, v209
	v_cndmask_b32_e32 v146, 0, v211, vcc
	v_cmp_lt_i32_e32 vcc, s67, v148
	v_or_b32_e32 v150, 56, v125
	s_and_b64 vcc, s[0:1], vcc
	v_sub_u32_e32 v150, v130, v150
	v_med3_i32 v149, v148, -1, v209
	v_cndmask_b32_e32 v148, 0, v211, vcc
	v_med3_i32 v151, v150, -1, v209
	v_cmp_lt_i32_e32 vcc, s67, v150
	v_or_b32_e32 v150, 57, v125
	s_and_b64 vcc, s[0:1], vcc
	v_sub_u32_e32 v150, v130, v150
	v_cndmask_b32_e32 v213, 0, v211, vcc
	v_med3_i32 v214, v150, -1, v209
	v_cmp_lt_i32_e32 vcc, s67, v150
	v_or_b32_e32 v150, 58, v125
	v_sub_u32_e32 v150, v130, v150
	v_or_b32_e32 v125, 59, v125
	s_and_b64 vcc, s[0:1], vcc
	v_med3_i32 v216, v150, -1, v209
	v_sub_u32_e32 v125, v130, v125
	v_lshl_add_u32 v131, v131, 2, s69
	v_lshl_add_u32 v145, v145, 2, s69
	v_lshl_add_u32 v147, v147, 2, s69
	v_lshl_add_u32 v149, v149, 2, s69
	v_lshl_add_u32 v214, v214, 2, s69
	v_cndmask_b32_e32 v215, 0, v211, vcc
	v_lshl_add_u32 v216, v216, 2, s69
	v_cmp_lt_i32_e32 vcc, s67, v150
	v_med3_i32 v150, v125, -1, v209
	v_lshl_add_u32 v151, v151, 2, s69
	v_lshl_add_u32 v150, v150, 2, s69
	ds_read_b32 v131, v131 offset:256
	ds_read_b32 v145, v145 offset:256
	ds_read_b32 v147, v147 offset:256
	ds_read_b32 v149, v149 offset:256
	ds_read_b32 v217, v151 offset:256
	ds_read_b32 v214, v214 offset:256
	ds_read_b32 v216, v216 offset:256
	ds_read_b32 v218, v150 offset:256
	s_and_b64 vcc, s[0:1], vcc
	v_cndmask_b32_e32 v219, 0, v211, vcc
	v_cmp_lt_i32_e32 vcc, s67, v125
	s_and_b64 vcc, s[0:1], vcc
	s_nop 0
	v_cndmask_b32_e32 v125, 0, v211, vcc
	s_waitcnt lgkmcnt(7)
	v_fmac_f32_e32 v131, 0x3fb8aa3b, v24
	s_waitcnt lgkmcnt(6)
	v_fmac_f32_e32 v145, 0x3fb8aa3b, v25
	v_add_f32_e32 v150, v129, v131
	v_add_f32_e32 v151, v144, v145
	s_waitcnt lgkmcnt(5)
	v_fmac_f32_e32 v147, 0x3fb8aa3b, v26
	s_waitcnt lgkmcnt(4)
	v_fmac_f32_e32 v149, 0x3fb8aa3b, v27
	v_max3_f32 v127, v127, v150, v151
	v_add_f32_e32 v146, v146, v147
	v_add_f32_e32 v147, v148, v149
	s_waitcnt lgkmcnt(3)
	v_fmac_f32_e32 v217, 0x3fb8aa3b, v28
	s_waitcnt lgkmcnt(2)
	v_fmac_f32_e32 v214, 0x3fb8aa3b, v29
	v_max3_f32 v127, v127, v146, v147
	v_add_f32_e32 v148, v213, v217
	v_add_f32_e32 v149, v215, v214
	s_waitcnt lgkmcnt(1)
	v_fmac_f32_e32 v216, 0x3fb8aa3b, v30
	s_waitcnt lgkmcnt(0)
	v_fmac_f32_e32 v218, 0x3fb8aa3b, v31
	v_max3_f32 v127, v127, v148, v149
	v_add_f32_e32 v144, v219, v216
	v_add_f32_e32 v145, v125, v218
	v_max3_f32 v129, v127, v144, v145
	s_mov_b64 s[2:3], 0

.Lfa_norescale2:
	v_exp_f32_e32 v0, v0
	v_exp_f32_e32 v1, v1
	v_add_f32_e32 v37, v0, v37
	v_exp_f32_e32 v2, v2
	v_add_f32_e32 v37, v1, v37
	v_exp_f32_e32 v3, v3
	v_add_f32_e32 v37, v2, v37
	v_exp_f32_e32 v4, v4
	v_add_f32_e32 v37, v3, v37
	v_exp_f32_e32 v5, v5
	v_add_f32_e32 v37, v4, v37
	v_exp_f32_e32 v6, v6
	v_add_f32_e32 v37, v5, v37
	v_exp_f32_e32 v7, v7
	v_add_f32_e32 v37, v6, v37
	s_nop 0
	v_add_f32_e32 v37, v7, v37
	v_cvt_pk_bf16_f32 v0, v0, v1
	v_cvt_pk_bf16_f32 v1, v2, v3
	v_cvt_pk_bf16_f32 v2, v4, v5
	v_cvt_pk_bf16_f32 v3, v6, v7
	s_waitcnt lgkmcnt(14)
	s_nop 0
	s_setprio 1
	v_mfma_f32_32x32x16_bf16 v[64:79], v[236:239], v[0:3], v[64:79]
	s_waitcnt lgkmcnt(12)
	v_mfma_f32_32x32x16_bf16 v[48:63], v[240:243], v[0:3], v[48:63]
	s_setprio 0
	v_exp_f32_e32 v8, v8
	v_exp_f32_e32 v9, v9
	v_add_f32_e32 v37, v8, v37
	v_exp_f32_e32 v10, v10
	v_add_f32_e32 v37, v9, v37
	v_exp_f32_e32 v11, v11
	v_add_f32_e32 v37, v10, v37
	v_exp_f32_e32 v12, v12
	v_add_f32_e32 v37, v11, v37
	v_exp_f32_e32 v13, v13
	v_add_f32_e32 v37, v12, v37
	v_exp_f32_e32 v14, v14
	v_add_f32_e32 v37, v13, v37
	v_exp_f32_e32 v15, v15
	v_add_f32_e32 v37, v14, v37
	s_nop 0
	v_add_f32_e32 v37, v15, v37
	v_cvt_pk_bf16_f32 v8, v8, v9
	v_cvt_pk_bf16_f32 v9, v10, v11
	v_cvt_pk_bf16_f32 v10, v12, v13
	v_cvt_pk_bf16_f32 v11, v14, v15
	s_waitcnt lgkmcnt(10)
	s_nop 0
	s_setprio 1
	v_mfma_f32_32x32x16_bf16 v[64:79], v[244:247], v[8:11], v[64:79]
	s_waitcnt lgkmcnt(8)
	v_mfma_f32_32x32x16_bf16 v[48:63], v[248:251], v[8:11], v[48:63]
	s_setprio 0
	v_exp_f32_e32 v16, v16
	v_exp_f32_e32 v17, v17
	v_add_f32_e32 v37, v16, v37
	v_exp_f32_e32 v18, v18
	v_add_f32_e32 v37, v17, v37
	v_exp_f32_e32 v19, v19
	v_add_f32_e32 v37, v18, v37
	v_exp_f32_e32 v20, v20
	v_add_f32_e32 v37, v19, v37
	v_exp_f32_e32 v21, v21
	v_add_f32_e32 v37, v20, v37
	v_exp_f32_e32 v22, v22
	v_add_f32_e32 v37, v21, v37
	v_exp_f32_e32 v23, v23
	v_add_f32_e32 v37, v22, v37
	s_nop 0
	v_add_f32_e32 v37, v23, v37
	v_cvt_pk_bf16_f32 v16, v16, v17
	v_cvt_pk_bf16_f32 v17, v18, v19
	v_cvt_pk_bf16_f32 v18, v20, v21
	v_cvt_pk_bf16_f32 v19, v22, v23
	s_waitcnt lgkmcnt(6)
	s_nop 0
	s_setprio 1
	v_mfma_f32_32x32x16_bf16 v[64:79], v[134:137], v[16:19], v[64:79]
	s_waitcnt lgkmcnt(4)
	v_mfma_f32_32x32x16_bf16 v[48:63], v[138:141], v[16:19], v[48:63]
	s_setprio 0
	v_exp_f32_e32 v24, v24
	v_exp_f32_e32 v25, v25
	v_add_f32_e32 v37, v24, v37
	v_exp_f32_e32 v26, v26
	v_add_f32_e32 v37, v25, v37
	v_exp_f32_e32 v27, v27
	v_add_f32_e32 v37, v26, v37
	v_exp_f32_e32 v28, v28
	v_add_f32_e32 v37, v27, v37
	v_exp_f32_e32 v29, v29
	v_add_f32_e32 v37, v28, v37
	v_exp_f32_e32 v30, v30
	v_add_f32_e32 v37, v29, v37
	v_exp_f32_e32 v31, v31
	v_add_f32_e32 v37, v30, v37
	s_nop 0
	v_add_f32_e32 v37, v31, v37
	v_cvt_pk_bf16_f32 v24, v24, v25
	v_cvt_pk_bf16_f32 v25, v26, v27
	v_cvt_pk_bf16_f32 v26, v28, v29
	v_cvt_pk_bf16_f32 v27, v30, v31
	s_waitcnt lgkmcnt(2)
	s_nop 0
	s_setprio 1
	v_mfma_f32_32x32x16_bf16 v[64:79], v[142:145], v[24:27], v[64:79]
	s_waitcnt lgkmcnt(0)
	v_mfma_f32_32x32x16_bf16 v[48:63], v[146:149], v[24:27], v[48:63]
	s_setprio 0
	v_fmac_f32_e32 v37, v121, v34
	v_mov_b32_e32 v123, v33
	v_mov_b32_e32 v121, v37

.Lfa_norescale:
	v_fmamk_f32 v0, v0, 0x3fb8aa3b, v36
	v_fmamk_f32 v1, v1, 0x3fb8aa3b, v36
	v_fmamk_f32 v2, v2, 0x3fb8aa3b, v36
	v_fmamk_f32 v3, v3, 0x3fb8aa3b, v36
	v_fmamk_f32 v4, v4, 0x3fb8aa3b, v36
	v_fmamk_f32 v5, v5, 0x3fb8aa3b, v36
	v_fmamk_f32 v6, v6, 0x3fb8aa3b, v36
	v_fmamk_f32 v7, v7, 0x3fb8aa3b, v36
	v_exp_f32_e32 v0, v0
	v_exp_f32_e32 v1, v1
	v_add_f32_e32 v37, v0, v37
	v_exp_f32_e32 v2, v2
	v_add_f32_e32 v37, v1, v37
	v_exp_f32_e32 v3, v3
	v_add_f32_e32 v37, v2, v37
	v_exp_f32_e32 v4, v4
	v_add_f32_e32 v37, v3, v37
	v_exp_f32_e32 v5, v5
	v_add_f32_e32 v37, v4, v37
	v_exp_f32_e32 v6, v6
	v_add_f32_e32 v37, v5, v37
	v_exp_f32_e32 v7, v7
	v_add_f32_e32 v37, v6, v37
	s_nop 0
	v_add_f32_e32 v37, v7, v37
	v_cvt_pk_bf16_f32 v0, v0, v1
	v_cvt_pk_bf16_f32 v1, v2, v3
	v_cvt_pk_bf16_f32 v2, v4, v5
	v_cvt_pk_bf16_f32 v3, v6, v7
	s_waitcnt lgkmcnt(14)
	s_nop 0
	s_setprio 1
	v_mfma_f32_32x32x16_bf16 v[64:79], v[134:137], v[0:3], v[64:79]
	s_waitcnt lgkmcnt(12)
	v_mfma_f32_32x32x16_bf16 v[48:63], v[138:141], v[0:3], v[48:63]
	s_setprio 0
	v_fmamk_f32 v8, v8, 0x3fb8aa3b, v36
	v_fmamk_f32 v9, v9, 0x3fb8aa3b, v36
	v_fmamk_f32 v10, v10, 0x3fb8aa3b, v36
	v_fmamk_f32 v11, v11, 0x3fb8aa3b, v36
	v_fmamk_f32 v12, v12, 0x3fb8aa3b, v36
	v_fmamk_f32 v13, v13, 0x3fb8aa3b, v36
	v_fmamk_f32 v14, v14, 0x3fb8aa3b, v36
	v_fmamk_f32 v15, v15, 0x3fb8aa3b, v36
	v_exp_f32_e32 v8, v8
	v_exp_f32_e32 v9, v9
	v_add_f32_e32 v37, v8, v37
	v_exp_f32_e32 v10, v10
	v_add_f32_e32 v37, v9, v37
	v_exp_f32_e32 v11, v11
	v_add_f32_e32 v37, v10, v37
	v_exp_f32_e32 v12, v12
	v_add_f32_e32 v37, v11, v37
	v_exp_f32_e32 v13, v13
	v_add_f32_e32 v37, v12, v37
	v_exp_f32_e32 v14, v14
	v_add_f32_e32 v37, v13, v37
	v_exp_f32_e32 v15, v15
	v_add_f32_e32 v37, v14, v37
	s_nop 0
	v_add_f32_e32 v37, v15, v37
	v_cvt_pk_bf16_f32 v8, v8, v9
	v_cvt_pk_bf16_f32 v9, v10, v11
	v_cvt_pk_bf16_f32 v10, v12, v13
	v_cvt_pk_bf16_f32 v11, v14, v15
	s_waitcnt lgkmcnt(10)
	s_nop 0
	s_setprio 1
	v_mfma_f32_32x32x16_bf16 v[64:79], v[142:145], v[8:11], v[64:79]
	s_waitcnt lgkmcnt(8)
	v_mfma_f32_32x32x16_bf16 v[48:63], v[146:149], v[8:11], v[48:63]
	s_setprio 0
	v_fmamk_f32 v16, v16, 0x3fb8aa3b, v36
	v_fmamk_f32 v17, v17, 0x3fb8aa3b, v36
	v_fmamk_f32 v18, v18, 0x3fb8aa3b, v36
	v_fmamk_f32 v19, v19, 0x3fb8aa3b, v36
	v_fmamk_f32 v20, v20, 0x3fb8aa3b, v36
	v_fmamk_f32 v21, v21, 0x3fb8aa3b, v36
	v_fmamk_f32 v22, v22, 0x3fb8aa3b, v36
	v_fmamk_f32 v23, v23, 0x3fb8aa3b, v36
	v_exp_f32_e32 v16, v16
	v_exp_f32_e32 v17, v17
	v_add_f32_e32 v37, v16, v37
	v_exp_f32_e32 v18, v18
	v_add_f32_e32 v37, v17, v37
	v_exp_f32_e32 v19, v19
	v_add_f32_e32 v37, v18, v37
	v_exp_f32_e32 v20, v20
	v_add_f32_e32 v37, v19, v37
	v_exp_f32_e32 v21, v21
	v_add_f32_e32 v37, v20, v37
	v_exp_f32_e32 v22, v22
	v_add_f32_e32 v37, v21, v37
	v_exp_f32_e32 v23, v23
	v_add_f32_e32 v37, v22, v37
	s_nop 0
	v_add_f32_e32 v37, v23, v37
	v_cvt_pk_bf16_f32 v16, v16, v17
	v_cvt_pk_bf16_f32 v17, v18, v19
	v_cvt_pk_bf16_f32 v18, v20, v21
	v_cvt_pk_bf16_f32 v19, v22, v23
	s_waitcnt lgkmcnt(6)
	s_nop 0
	s_setprio 1
	v_mfma_f32_32x32x16_bf16 v[64:79], v[236:239], v[16:19], v[64:79]
	s_waitcnt lgkmcnt(4)
	v_mfma_f32_32x32x16_bf16 v[48:63], v[240:243], v[16:19], v[48:63]
	s_setprio 0
	v_fmamk_f32 v24, v24, 0x3fb8aa3b, v36
	v_fmamk_f32 v25, v25, 0x3fb8aa3b, v36
	v_fmamk_f32 v26, v26, 0x3fb8aa3b, v36
	v_fmamk_f32 v27, v27, 0x3fb8aa3b, v36
	v_fmamk_f32 v28, v28, 0x3fb8aa3b, v36
	v_fmamk_f32 v29, v29, 0x3fb8aa3b, v36
	v_fmamk_f32 v30, v30, 0x3fb8aa3b, v36
	v_fmamk_f32 v31, v31, 0x3fb8aa3b, v36
	v_exp_f32_e32 v24, v24
	v_exp_f32_e32 v25, v25
	v_add_f32_e32 v37, v24, v37
	v_exp_f32_e32 v26, v26
	v_add_f32_e32 v37, v25, v37
	v_exp_f32_e32 v27, v27
	v_add_f32_e32 v37, v26, v37
	v_exp_f32_e32 v28, v28
	v_add_f32_e32 v37, v27, v37
	v_exp_f32_e32 v29, v29
	v_add_f32_e32 v37, v28, v37
	v_exp_f32_e32 v30, v30
	v_add_f32_e32 v37, v29, v37
	v_exp_f32_e32 v31, v31
	v_add_f32_e32 v37, v30, v37
	s_nop 0
	v_add_f32_e32 v37, v31, v37
	v_cvt_pk_bf16_f32 v24, v24, v25
	v_cvt_pk_bf16_f32 v25, v26, v27
	v_cvt_pk_bf16_f32 v26, v28, v29
	v_cvt_pk_bf16_f32 v27, v30, v31
	s_waitcnt lgkmcnt(2)
	s_nop 0
	s_setprio 1
	v_mfma_f32_32x32x16_bf16 v[64:79], v[244:247], v[24:27], v[64:79]
	s_waitcnt lgkmcnt(0)
	v_mfma_f32_32x32x16_bf16 v[48:63], v[248:251], v[24:27], v[48:63]
	s_setprio 0
	v_fmac_f32_e32 v37, v121, v34
	v_mov_b32_e32 v123, v33
	v_mov_b32_e32 v121, v37
	s_branch .LBB0_1470
